# code placement: all code after P0(b) shifted by -32 bytes (skip pad 28 instead of 60)
# speedup vs baseline: 1.0024x; 1.0013x over previous
.LBB0_32:
	s_or_b64 exec, exec, s[0:1]
	s_movk_i32 s0, 0x600
	v_cmp_gt_i32_e32 vcc, s0, v66
	s_waitcnt lgkmcnt(0)
	s_barrier
	s_and_saveexec_b64 s[8:9], vcc
	s_cbranch_execz .LBB0_39
	v_and_b32_e32 v71, 15, v64
	v_lshrrev_b32_e32 v72, 4, v64
	v_readfirstlane_b32 s24, v66
	v_lshlrev_b32_e32 v67, 8, v72
	v_lshl_add_u32 v67, v71, 2, v67
	v_lshlrev_b32_e32 v70, 4, v72
	ds_read_b128 v[20:23], v70 offset:41984
	ds_read_b128 v[24:27], v70 offset:42048
	ds_read_b128 v[28:31], v70 offset:42112
	ds_read_b128 v[32:35], v70 offset:42176
	v_mul_u32_u24_e32 v73, 0x110, v71
	v_mul_u32_u24_e32 v74, 0x1100, v200
	v_add_u32_e32 v74, 0xa800, v74
	v_add_u32_e32 v73, v73, v74
	v_lshl_add_u32 v68, v72, 2, v73
	v_lshl_add_u32 v69, v72, 4, v73
	s_lshl_b32 s25, s24, 4
	s_mov_b32 s30, 0x38800000
	s_mov_b32 s31, 0x39000000
	s_mov_b32 s0, 0x467ffc00
	s_mov_b32 s1, 0x45fff800
	s_cmp_lt_u32 s25, 0x4000
	s_cselect_b32 s30, s30, s31
	s_cselect_b32 s31, s0, s1
	s_cselect_b32 s26, 0, 0x4000
	s_sub_u32 s27, s25, s26
	v_add_u32_e32 v75, s27, v71
	v_cvt_f32_i32_e32 v75, v75
	v_mov_b32_e32 v76, s31
	v_div_scale_f32 v82, s[36:37], v76, v76, v75
	v_rcp_f32_e32 v83, v82
	v_div_scale_f32 v84, vcc, v75, v76, v75
	v_fma_f32 v85, -v82, v83, 1.0
	v_fmac_f32_e32 v83, v85, v83
	v_mul_f32_e32 v85, v84, v83
	v_fma_f32 v86, -v82, v85, v84
	v_fmac_f32_e32 v85, v86, v83
	v_fma_f32 v82, -v82, v85, v84
	v_div_fmas_f32 v82, v82, v83, v85
	v_div_fixup_f32 v77, v82, v76, v75
	v_cmp_eq_u32_e64 s[0:1], 0, v72
	v_add_u32_e32 v78, -1, v72
	v_and_b32_e32 v78, 15, v78
	v_cvt_f32_ubyte0_e32 v78, v78
	v_mov_b32_e32 v79, 0x38d1b717
	v_fmac_f32_e32 v79, 0x3f7fff90, v78
	v_mul_f32_e32 v79, v79, v75
	v_mul_f32_e32 v79, s30, v79
	v_cos_f32_e32 v80, v79
	v_sin_f32_e64 v81, -v79
	v_add_u32_e32 v78, 3, v72
	v_and_b32_e32 v78, 15, v78
	v_cvt_f32_ubyte0_e32 v78, v78
	v_mov_b32_e32 v79, 0x38d1b717
	v_fmac_f32_e32 v79, 0x3f7fff90, v78
	v_mul_f32_e32 v79, v79, v75
	v_mul_f32_e32 v79, s30, v79
	v_cos_f32_e32 v37, v79
	v_sin_f32_e64 v41, -v79
	v_add_u32_e32 v78, 7, v72
	v_and_b32_e32 v78, 15, v78
	v_cvt_f32_ubyte0_e32 v78, v78
	v_mov_b32_e32 v79, 0x38d1b717
	v_fmac_f32_e32 v79, 0x3f7fff90, v78
	v_mul_f32_e32 v79, v79, v75
	v_mul_f32_e32 v79, s30, v79
	v_cos_f32_e32 v38, v79
	v_sin_f32_e64 v42, -v79
	v_add_u32_e32 v78, 11, v72
	v_and_b32_e32 v78, 15, v78
	v_cvt_f32_ubyte0_e32 v78, v78
	v_mov_b32_e32 v79, 0x38d1b717
	v_fmac_f32_e32 v79, 0x3f7fff90, v78
	v_mul_f32_e32 v79, v79, v75
	v_mul_f32_e32 v79, s30, v79
	v_cos_f32_e32 v39, v79
	v_sin_f32_e64 v43, -v79
	s_nop 0
	v_cndmask_b32_e64 v36, v80, v77, s[0:1]
	v_cndmask_b32_e64 v40, v81, v80, s[0:1]
	v_cndmask_b32_e64 v44, 0, v81, s[0:1]
	s_waitcnt lgkmcnt(0)
	v_mul_f32_e32 v20, 0.15915494, v20
	v_mul_f32_e32 v21, 0.15915494, v21
	v_mul_f32_e32 v22, 0.15915494, v22
	v_mul_f32_e32 v23, 0.15915494, v23
	v_mul_f32_e32 v24, 0.15915494, v24
	v_mul_f32_e32 v25, 0.15915494, v25
	v_mul_f32_e32 v26, 0.15915494, v26
	v_mul_f32_e32 v27, 0.15915494, v27
	v_mul_f32_e32 v28, 0.15915494, v28
	v_mul_f32_e32 v29, 0.15915494, v29
	v_mul_f32_e32 v30, 0.15915494, v30
	v_mul_f32_e32 v31, 0.15915494, v31
	v_mul_f32_e32 v32, 0.15915494, v32
	v_mul_f32_e32 v33, 0.15915494, v33
	v_mul_f32_e32 v34, 0.15915494, v34
	v_mul_f32_e32 v35, 0.15915494, v35
	s_add_u32 s26, s56, 0x1e420000
	s_addc_u32 s27, s57, 0
	s_lshl_b32 s4, s24, 11
	s_add_u32 s26, s26, s4
	s_addc_u32 s27, s27, 0
	v_lshlrev_b32_e32 v92, 7, v71
	v_lshl_add_u32 v92, v72, 3, v92
	s_mov_b32 s30, 0x7fff
	s_mov_b32 s31, 0x7060302
	ds_read_b128 v[4:7], v70 offset:41216
	ds_read_b128 v[8:11], v70 offset:41280
	ds_read_b128 v[12:15], v70 offset:41344
	ds_read_b128 v[16:19], v70 offset:41408
	ds_read_b32 v45, v67 offset:0
	ds_read_b32 v46, v67 offset:64
	ds_read_b32 v47, v67 offset:128
	ds_read_b32 v48, v67 offset:192
	ds_read_b32 v50, v67 offset:1024
	ds_read_b32 v51, v67 offset:1088
	ds_read_b32 v52, v67 offset:1152
	ds_read_b32 v53, v67 offset:1216
	s_waitcnt lgkmcnt(4)
	v_mfma_f32_16x16x4_f32 v[4:7], v45, v36, v[4:7]
	ds_read_b32 v55, v67 offset:2048
	ds_read_b32 v56, v67 offset:2112
	ds_read_b32 v57, v67 offset:2176
	ds_read_b32 v58, v67 offset:2240
	v_mfma_f32_16x16x4_f32 v[8:11], v46, v36, v[8:11]
	v_mfma_f32_16x16x4_f32 v[12:15], v47, v36, v[12:15]
	v_mfma_f32_16x16x4_f32 v[16:19], v48, v36, v[16:19]
	s_waitcnt lgkmcnt(4)
	v_mfma_f32_16x16x4_f32 v[4:7], v50, v37, v[4:7]
	ds_read_b32 v45, v67 offset:3072
	ds_read_b32 v46, v67 offset:3136
	ds_read_b32 v47, v67 offset:3200
	ds_read_b32 v48, v67 offset:3264
	v_mfma_f32_16x16x4_f32 v[8:11], v51, v37, v[8:11]
	v_mfma_f32_16x16x4_f32 v[12:15], v52, v37, v[12:15]
	v_mfma_f32_16x16x4_f32 v[16:19], v53, v37, v[16:19]
	s_waitcnt lgkmcnt(4)
	v_mfma_f32_16x16x4_f32 v[4:7], v55, v38, v[4:7]
	ds_read_b32 v50, v67 offset:4096
	ds_read_b32 v51, v67 offset:4160
	ds_read_b32 v52, v67 offset:4224
	ds_read_b32 v53, v67 offset:4288
	v_mfma_f32_16x16x4_f32 v[8:11], v56, v38, v[8:11]
	v_mfma_f32_16x16x4_f32 v[12:15], v57, v38, v[12:15]
	v_mfma_f32_16x16x4_f32 v[16:19], v58, v38, v[16:19]
	s_waitcnt lgkmcnt(4)
	v_mfma_f32_16x16x4_f32 v[4:7], v45, v39, v[4:7]
	ds_read_b32 v55, v67 offset:5120
	ds_read_b32 v56, v67 offset:5184
	ds_read_b32 v57, v67 offset:5248
	ds_read_b32 v58, v67 offset:5312
	v_mfma_f32_16x16x4_f32 v[8:11], v46, v39, v[8:11]
	v_mfma_f32_16x16x4_f32 v[12:15], v47, v39, v[12:15]
	v_mfma_f32_16x16x4_f32 v[16:19], v48, v39, v[16:19]
	s_waitcnt lgkmcnt(4)
	v_mfma_f32_16x16x4_f32 v[4:7], v50, v40, v[4:7]
	ds_read_b32 v45, v67 offset:6144
	ds_read_b32 v46, v67 offset:6208
	ds_read_b32 v47, v67 offset:6272
	ds_read_b32 v48, v67 offset:6336
	v_mfma_f32_16x16x4_f32 v[8:11], v51, v40, v[8:11]
	v_mfma_f32_16x16x4_f32 v[12:15], v52, v40, v[12:15]
	v_mfma_f32_16x16x4_f32 v[16:19], v53, v40, v[16:19]
	s_waitcnt lgkmcnt(4)
	v_mfma_f32_16x16x4_f32 v[4:7], v55, v41, v[4:7]
	ds_read_b32 v50, v67 offset:7168
	ds_read_b32 v51, v67 offset:7232
	ds_read_b32 v52, v67 offset:7296
	ds_read_b32 v53, v67 offset:7360
	v_mfma_f32_16x16x4_f32 v[8:11], v56, v41, v[8:11]
	v_mfma_f32_16x16x4_f32 v[12:15], v57, v41, v[12:15]
	v_mfma_f32_16x16x4_f32 v[16:19], v58, v41, v[16:19]
	s_waitcnt lgkmcnt(4)
	v_mfma_f32_16x16x4_f32 v[4:7], v45, v42, v[4:7]
	ds_read_b32 v55, v67 offset:8192
	ds_read_b32 v56, v67 offset:8256
	ds_read_b32 v57, v67 offset:8320
	ds_read_b32 v58, v67 offset:8384
	v_mfma_f32_16x16x4_f32 v[8:11], v46, v42, v[8:11]
	v_mfma_f32_16x16x4_f32 v[12:15], v47, v42, v[12:15]
	v_mfma_f32_16x16x4_f32 v[16:19], v48, v42, v[16:19]
	s_waitcnt lgkmcnt(4)
	v_mfma_f32_16x16x4_f32 v[4:7], v50, v43, v[4:7]
	v_mfma_f32_16x16x4_f32 v[8:11], v51, v43, v[8:11]
	v_mfma_f32_16x16x4_f32 v[12:15], v52, v43, v[12:15]
	v_mfma_f32_16x16x4_f32 v[16:19], v53, v43, v[16:19]
	s_waitcnt lgkmcnt(0)
	v_mfma_f32_16x16x4_f32 v[4:7], v55, v44, v[4:7]
	v_mfma_f32_16x16x4_f32 v[8:11], v56, v44, v[8:11]
	v_mfma_f32_16x16x4_f32 v[12:15], v57, v44, v[12:15]
	v_mfma_f32_16x16x4_f32 v[16:19], v58, v44, v[16:19]
	s_nop 7
	s_nop 3
	v_mul_f32_e32 v4, v20, v4
	v_mul_f32_e32 v5, v21, v5
	v_mul_f32_e32 v6, v22, v6
	v_mul_f32_e32 v7, v23, v7
	v_mul_f32_e32 v8, v24, v8
	v_mul_f32_e32 v9, v25, v9
	v_mul_f32_e32 v10, v26, v10
	v_mul_f32_e32 v11, v27, v11
	v_mul_f32_e32 v12, v28, v12
	v_mul_f32_e32 v13, v29, v13
	v_mul_f32_e32 v14, v30, v14
	v_mul_f32_e32 v15, v31, v15
	v_mul_f32_e32 v16, v32, v16
	v_mul_f32_e32 v17, v33, v17
	v_mul_f32_e32 v18, v34, v18
	v_mul_f32_e32 v19, v35, v19
	v_sin_f32_e32 v4, v4
	v_sin_f32_e32 v5, v5
	v_sin_f32_e32 v6, v6
	v_sin_f32_e32 v7, v7
	v_sin_f32_e32 v8, v8
	v_sin_f32_e32 v9, v9
	v_sin_f32_e32 v10, v10
	v_sin_f32_e32 v11, v11
	v_sin_f32_e32 v12, v12
	v_sin_f32_e32 v13, v13
	v_sin_f32_e32 v14, v14
	v_sin_f32_e32 v15, v15
	v_sin_f32_e32 v16, v16
	v_sin_f32_e32 v17, v17
	v_sin_f32_e32 v18, v18
	v_sin_f32_e32 v19, v19
	s_nop 1
	ds_write_b128 v69, v[4:7] offset:0
	ds_write_b128 v69, v[8:11] offset:64
	ds_write_b128 v69, v[12:15] offset:128
	ds_write_b128 v69, v[16:19] offset:192
	s_waitcnt lgkmcnt(0)
	ds_read_b128 v[100:103], v70 offset:41472
	ds_read_b128 v[104:107], v70 offset:41536
	ds_read_b128 v[108:111], v70 offset:41600
	ds_read_b128 v[112:115], v70 offset:41664
	ds_read_b32 v49, v68 offset:0
	ds_read_b32 v45, v67 offset:8448
	ds_read_b32 v46, v67 offset:8512
	ds_read_b32 v47, v67 offset:8576
	ds_read_b32 v48, v67 offset:8640
	ds_read_b32 v54, v68 offset:16
	ds_read_b32 v50, v67 offset:9472
	ds_read_b32 v51, v67 offset:9536
	ds_read_b32 v52, v67 offset:9600
	ds_read_b32 v53, v67 offset:9664
	s_waitcnt lgkmcnt(5)
	v_mfma_f32_16x16x4_f32 v[100:103], v45, v49, v[100:103]
	ds_read_b32 v59, v68 offset:32
	ds_read_b32 v55, v67 offset:10496
	ds_read_b32 v56, v67 offset:10560
	ds_read_b32 v57, v67 offset:10624
	ds_read_b32 v58, v67 offset:10688
	v_mfma_f32_16x16x4_f32 v[104:107], v46, v49, v[104:107]
	v_mfma_f32_16x16x4_f32 v[108:111], v47, v49, v[108:111]
	v_mfma_f32_16x16x4_f32 v[112:115], v48, v49, v[112:115]
	s_waitcnt lgkmcnt(5)
	v_mfma_f32_16x16x4_f32 v[100:103], v50, v54, v[100:103]
	ds_read_b32 v49, v68 offset:48
	ds_read_b32 v45, v67 offset:11520
	ds_read_b32 v46, v67 offset:11584
	ds_read_b32 v47, v67 offset:11648
	ds_read_b32 v48, v67 offset:11712
	v_mfma_f32_16x16x4_f32 v[104:107], v51, v54, v[104:107]
	v_mfma_f32_16x16x4_f32 v[108:111], v52, v54, v[108:111]
	v_mfma_f32_16x16x4_f32 v[112:115], v53, v54, v[112:115]
	s_waitcnt lgkmcnt(5)
	v_mfma_f32_16x16x4_f32 v[100:103], v55, v59, v[100:103]
	ds_read_b32 v54, v68 offset:64
	ds_read_b32 v50, v67 offset:12544
	ds_read_b32 v51, v67 offset:12608
	ds_read_b32 v52, v67 offset:12672
	ds_read_b32 v53, v67 offset:12736
	v_mfma_f32_16x16x4_f32 v[104:107], v56, v59, v[104:107]
	v_mfma_f32_16x16x4_f32 v[108:111], v57, v59, v[108:111]
	v_mfma_f32_16x16x4_f32 v[112:115], v58, v59, v[112:115]
	s_waitcnt lgkmcnt(5)
	v_mfma_f32_16x16x4_f32 v[100:103], v45, v49, v[100:103]
	ds_read_b32 v59, v68 offset:80
	ds_read_b32 v55, v67 offset:13568
	ds_read_b32 v56, v67 offset:13632
	ds_read_b32 v57, v67 offset:13696
	ds_read_b32 v58, v67 offset:13760
	v_mfma_f32_16x16x4_f32 v[104:107], v46, v49, v[104:107]
	v_mfma_f32_16x16x4_f32 v[108:111], v47, v49, v[108:111]
	v_mfma_f32_16x16x4_f32 v[112:115], v48, v49, v[112:115]
	s_waitcnt lgkmcnt(5)
	v_mfma_f32_16x16x4_f32 v[100:103], v50, v54, v[100:103]
	ds_read_b32 v49, v68 offset:96
	ds_read_b32 v45, v67 offset:14592
	ds_read_b32 v46, v67 offset:14656
	ds_read_b32 v47, v67 offset:14720
	ds_read_b32 v48, v67 offset:14784
	v_mfma_f32_16x16x4_f32 v[104:107], v51, v54, v[104:107]
	v_mfma_f32_16x16x4_f32 v[108:111], v52, v54, v[108:111]
	v_mfma_f32_16x16x4_f32 v[112:115], v53, v54, v[112:115]
	s_waitcnt lgkmcnt(5)
	v_mfma_f32_16x16x4_f32 v[100:103], v55, v59, v[100:103]
	ds_read_b32 v54, v68 offset:112
	ds_read_b32 v50, v67 offset:15616
	ds_read_b32 v51, v67 offset:15680
	ds_read_b32 v52, v67 offset:15744
	ds_read_b32 v53, v67 offset:15808
	v_mfma_f32_16x16x4_f32 v[104:107], v56, v59, v[104:107]
	v_mfma_f32_16x16x4_f32 v[108:111], v57, v59, v[108:111]
	v_mfma_f32_16x16x4_f32 v[112:115], v58, v59, v[112:115]
	s_waitcnt lgkmcnt(5)
	v_mfma_f32_16x16x4_f32 v[100:103], v45, v49, v[100:103]
	ds_read_b32 v59, v68 offset:128
	ds_read_b32 v55, v67 offset:16640
	ds_read_b32 v56, v67 offset:16704
	ds_read_b32 v57, v67 offset:16768
	ds_read_b32 v58, v67 offset:16832
	v_mfma_f32_16x16x4_f32 v[104:107], v46, v49, v[104:107]
	v_mfma_f32_16x16x4_f32 v[108:111], v47, v49, v[108:111]
	v_mfma_f32_16x16x4_f32 v[112:115], v48, v49, v[112:115]
	s_waitcnt lgkmcnt(5)
	v_mfma_f32_16x16x4_f32 v[100:103], v50, v54, v[100:103]
	ds_read_b32 v49, v68 offset:144
	ds_read_b32 v45, v67 offset:17664
	ds_read_b32 v46, v67 offset:17728
	ds_read_b32 v47, v67 offset:17792
	ds_read_b32 v48, v67 offset:17856
	v_mfma_f32_16x16x4_f32 v[104:107], v51, v54, v[104:107]
	v_mfma_f32_16x16x4_f32 v[108:111], v52, v54, v[108:111]
	v_mfma_f32_16x16x4_f32 v[112:115], v53, v54, v[112:115]
	s_waitcnt lgkmcnt(5)
	v_mfma_f32_16x16x4_f32 v[100:103], v55, v59, v[100:103]
	ds_read_b32 v54, v68 offset:160
	ds_read_b32 v50, v67 offset:18688
	ds_read_b32 v51, v67 offset:18752
	ds_read_b32 v52, v67 offset:18816
	ds_read_b32 v53, v67 offset:18880
	v_mfma_f32_16x16x4_f32 v[104:107], v56, v59, v[104:107]
	v_mfma_f32_16x16x4_f32 v[108:111], v57, v59, v[108:111]
	v_mfma_f32_16x16x4_f32 v[112:115], v58, v59, v[112:115]
	s_waitcnt lgkmcnt(5)
	v_mfma_f32_16x16x4_f32 v[100:103], v45, v49, v[100:103]
	ds_read_b32 v59, v68 offset:176
	ds_read_b32 v55, v67 offset:19712
	ds_read_b32 v56, v67 offset:19776
	ds_read_b32 v57, v67 offset:19840
	ds_read_b32 v58, v67 offset:19904
	v_mfma_f32_16x16x4_f32 v[104:107], v46, v49, v[104:107]
	v_mfma_f32_16x16x4_f32 v[108:111], v47, v49, v[108:111]
	v_mfma_f32_16x16x4_f32 v[112:115], v48, v49, v[112:115]
	s_waitcnt lgkmcnt(5)
	v_mfma_f32_16x16x4_f32 v[100:103], v50, v54, v[100:103]
	ds_read_b32 v49, v68 offset:192
	ds_read_b32 v45, v67 offset:20736
	ds_read_b32 v46, v67 offset:20800
	ds_read_b32 v47, v67 offset:20864
	ds_read_b32 v48, v67 offset:20928
	v_mfma_f32_16x16x4_f32 v[104:107], v51, v54, v[104:107]
	v_mfma_f32_16x16x4_f32 v[108:111], v52, v54, v[108:111]
	v_mfma_f32_16x16x4_f32 v[112:115], v53, v54, v[112:115]
	s_waitcnt lgkmcnt(5)
	v_mfma_f32_16x16x4_f32 v[100:103], v55, v59, v[100:103]
	ds_read_b32 v54, v68 offset:208
	ds_read_b32 v50, v67 offset:21760
	ds_read_b32 v51, v67 offset:21824
	ds_read_b32 v52, v67 offset:21888
	ds_read_b32 v53, v67 offset:21952
	v_mfma_f32_16x16x4_f32 v[104:107], v56, v59, v[104:107]
	v_mfma_f32_16x16x4_f32 v[108:111], v57, v59, v[108:111]
	v_mfma_f32_16x16x4_f32 v[112:115], v58, v59, v[112:115]
	s_waitcnt lgkmcnt(5)
	v_mfma_f32_16x16x4_f32 v[100:103], v45, v49, v[100:103]
	ds_read_b32 v59, v68 offset:224
	ds_read_b32 v55, v67 offset:22784
	ds_read_b32 v56, v67 offset:22848
	ds_read_b32 v57, v67 offset:22912
	ds_read_b32 v58, v67 offset:22976
	v_mfma_f32_16x16x4_f32 v[104:107], v46, v49, v[104:107]
	v_mfma_f32_16x16x4_f32 v[108:111], v47, v49, v[108:111]
	v_mfma_f32_16x16x4_f32 v[112:115], v48, v49, v[112:115]
	s_waitcnt lgkmcnt(5)
	v_mfma_f32_16x16x4_f32 v[100:103], v50, v54, v[100:103]
	ds_read_b32 v49, v68 offset:240
	ds_read_b32 v45, v67 offset:23808
	ds_read_b32 v46, v67 offset:23872
	ds_read_b32 v47, v67 offset:23936
	ds_read_b32 v48, v67 offset:24000
	v_mfma_f32_16x16x4_f32 v[104:107], v51, v54, v[104:107]
	v_mfma_f32_16x16x4_f32 v[108:111], v52, v54, v[108:111]
	v_mfma_f32_16x16x4_f32 v[112:115], v53, v54, v[112:115]
	s_waitcnt lgkmcnt(5)
	v_mfma_f32_16x16x4_f32 v[100:103], v55, v59, v[100:103]
	v_mfma_f32_16x16x4_f32 v[104:107], v56, v59, v[104:107]
	v_mfma_f32_16x16x4_f32 v[108:111], v57, v59, v[108:111]
	v_mfma_f32_16x16x4_f32 v[112:115], v58, v59, v[112:115]
	s_waitcnt lgkmcnt(0)
	v_mfma_f32_16x16x4_f32 v[100:103], v45, v49, v[100:103]
	v_mfma_f32_16x16x4_f32 v[104:107], v46, v49, v[104:107]
	v_mfma_f32_16x16x4_f32 v[108:111], v47, v49, v[108:111]
	v_mfma_f32_16x16x4_f32 v[112:115], v48, v49, v[112:115]
	s_nop 7
	s_nop 3
	v_mul_f32_e32 v100, v20, v100
	v_mul_f32_e32 v101, v21, v101
	v_mul_f32_e32 v102, v22, v102
	v_mul_f32_e32 v103, v23, v103
	v_mul_f32_e32 v104, v24, v104
	v_mul_f32_e32 v105, v25, v105
	v_mul_f32_e32 v106, v26, v106
	v_mul_f32_e32 v107, v27, v107
	v_mul_f32_e32 v108, v28, v108
	v_mul_f32_e32 v109, v29, v109
	v_mul_f32_e32 v110, v30, v110
	v_mul_f32_e32 v111, v31, v111
	v_mul_f32_e32 v112, v32, v112
	v_mul_f32_e32 v113, v33, v113
	v_mul_f32_e32 v114, v34, v114
	v_mul_f32_e32 v115, v35, v115
	v_sin_f32_e32 v100, v100
	v_sin_f32_e32 v101, v101
	v_sin_f32_e32 v102, v102
	v_sin_f32_e32 v103, v103
	v_sin_f32_e32 v104, v104
	v_sin_f32_e32 v105, v105
	v_sin_f32_e32 v106, v106
	v_sin_f32_e32 v107, v107
	v_sin_f32_e32 v108, v108
	v_sin_f32_e32 v109, v109
	v_sin_f32_e32 v110, v110
	v_sin_f32_e32 v111, v111
	v_sin_f32_e32 v112, v112
	v_sin_f32_e32 v113, v113
	v_sin_f32_e32 v114, v114
	v_sin_f32_e32 v115, v115
	s_nop 1
	ds_write_b128 v69, v[100:103] offset:0
	ds_write_b128 v69, v[104:107] offset:64
	ds_write_b128 v69, v[108:111] offset:128
	ds_write_b128 v69, v[112:115] offset:192
	s_waitcnt lgkmcnt(0)
	ds_read_b128 v[4:7], v70 offset:41728
	ds_read_b128 v[8:11], v70 offset:41792
	ds_read_b128 v[12:15], v70 offset:41856
	ds_read_b128 v[16:19], v70 offset:41920
	ds_read_b32 v49, v68 offset:0
	ds_read_b32 v45, v67 offset:24832
	ds_read_b32 v46, v67 offset:24896
	ds_read_b32 v47, v67 offset:24960
	ds_read_b32 v48, v67 offset:25024
	ds_read_b32 v54, v68 offset:16
	ds_read_b32 v50, v67 offset:25856
	ds_read_b32 v51, v67 offset:25920
	ds_read_b32 v52, v67 offset:25984
	ds_read_b32 v53, v67 offset:26048
	s_waitcnt lgkmcnt(5)
	v_mfma_f32_16x16x4_f32 v[4:7], v45, v49, v[4:7]
	ds_read_b32 v59, v68 offset:32
	ds_read_b32 v55, v67 offset:26880
	ds_read_b32 v56, v67 offset:26944
	ds_read_b32 v57, v67 offset:27008
	ds_read_b32 v58, v67 offset:27072
	v_mfma_f32_16x16x4_f32 v[8:11], v46, v49, v[8:11]
	v_mfma_f32_16x16x4_f32 v[12:15], v47, v49, v[12:15]
	v_mfma_f32_16x16x4_f32 v[16:19], v48, v49, v[16:19]
	s_waitcnt lgkmcnt(5)
	v_mfma_f32_16x16x4_f32 v[4:7], v50, v54, v[4:7]
	ds_read_b32 v49, v68 offset:48
	ds_read_b32 v45, v67 offset:27904
	ds_read_b32 v46, v67 offset:27968
	ds_read_b32 v47, v67 offset:28032
	ds_read_b32 v48, v67 offset:28096
	v_mfma_f32_16x16x4_f32 v[8:11], v51, v54, v[8:11]
	v_mfma_f32_16x16x4_f32 v[12:15], v52, v54, v[12:15]
	v_mfma_f32_16x16x4_f32 v[16:19], v53, v54, v[16:19]
	s_waitcnt lgkmcnt(5)
	v_mfma_f32_16x16x4_f32 v[4:7], v55, v59, v[4:7]
	ds_read_b32 v54, v68 offset:64
	ds_read_b32 v50, v67 offset:28928
	ds_read_b32 v51, v67 offset:28992
	ds_read_b32 v52, v67 offset:29056
	ds_read_b32 v53, v67 offset:29120
	v_mfma_f32_16x16x4_f32 v[8:11], v56, v59, v[8:11]
	v_mfma_f32_16x16x4_f32 v[12:15], v57, v59, v[12:15]
	v_mfma_f32_16x16x4_f32 v[16:19], v58, v59, v[16:19]
	s_waitcnt lgkmcnt(5)
	v_mfma_f32_16x16x4_f32 v[4:7], v45, v49, v[4:7]
	ds_read_b32 v59, v68 offset:80
	ds_read_b32 v55, v67 offset:29952
	ds_read_b32 v56, v67 offset:30016
	ds_read_b32 v57, v67 offset:30080
	ds_read_b32 v58, v67 offset:30144
	v_mfma_f32_16x16x4_f32 v[8:11], v46, v49, v[8:11]
	v_mfma_f32_16x16x4_f32 v[12:15], v47, v49, v[12:15]
	v_mfma_f32_16x16x4_f32 v[16:19], v48, v49, v[16:19]
	s_waitcnt lgkmcnt(5)
	v_mfma_f32_16x16x4_f32 v[4:7], v50, v54, v[4:7]
	ds_read_b32 v49, v68 offset:96
	ds_read_b32 v45, v67 offset:30976
	ds_read_b32 v46, v67 offset:31040
	ds_read_b32 v47, v67 offset:31104
	ds_read_b32 v48, v67 offset:31168
	v_mfma_f32_16x16x4_f32 v[8:11], v51, v54, v[8:11]
	v_mfma_f32_16x16x4_f32 v[12:15], v52, v54, v[12:15]
	v_mfma_f32_16x16x4_f32 v[16:19], v53, v54, v[16:19]
	s_waitcnt lgkmcnt(5)
	v_mfma_f32_16x16x4_f32 v[4:7], v55, v59, v[4:7]
	ds_read_b32 v54, v68 offset:112
	ds_read_b32 v50, v67 offset:32000
	ds_read_b32 v51, v67 offset:32064
	ds_read_b32 v52, v67 offset:32128
	ds_read_b32 v53, v67 offset:32192
	v_mfma_f32_16x16x4_f32 v[8:11], v56, v59, v[8:11]
	v_mfma_f32_16x16x4_f32 v[12:15], v57, v59, v[12:15]
	v_mfma_f32_16x16x4_f32 v[16:19], v58, v59, v[16:19]
	s_waitcnt lgkmcnt(5)
	v_mfma_f32_16x16x4_f32 v[4:7], v45, v49, v[4:7]
	ds_read_b32 v59, v68 offset:128
	ds_read_b32 v55, v67 offset:33024
	ds_read_b32 v56, v67 offset:33088
	ds_read_b32 v57, v67 offset:33152
	ds_read_b32 v58, v67 offset:33216
	v_mfma_f32_16x16x4_f32 v[8:11], v46, v49, v[8:11]
	v_mfma_f32_16x16x4_f32 v[12:15], v47, v49, v[12:15]
	v_mfma_f32_16x16x4_f32 v[16:19], v48, v49, v[16:19]
	s_waitcnt lgkmcnt(5)
	v_mfma_f32_16x16x4_f32 v[4:7], v50, v54, v[4:7]
	ds_read_b32 v49, v68 offset:144
	ds_read_b32 v45, v67 offset:34048
	ds_read_b32 v46, v67 offset:34112
	ds_read_b32 v47, v67 offset:34176
	ds_read_b32 v48, v67 offset:34240
	v_mfma_f32_16x16x4_f32 v[8:11], v51, v54, v[8:11]
	v_mfma_f32_16x16x4_f32 v[12:15], v52, v54, v[12:15]
	v_mfma_f32_16x16x4_f32 v[16:19], v53, v54, v[16:19]
	s_waitcnt lgkmcnt(5)
	v_mfma_f32_16x16x4_f32 v[4:7], v55, v59, v[4:7]
	ds_read_b32 v54, v68 offset:160
	ds_read_b32 v50, v67 offset:35072
	ds_read_b32 v51, v67 offset:35136
	ds_read_b32 v52, v67 offset:35200
	ds_read_b32 v53, v67 offset:35264
	v_mfma_f32_16x16x4_f32 v[8:11], v56, v59, v[8:11]
	v_mfma_f32_16x16x4_f32 v[12:15], v57, v59, v[12:15]
	v_mfma_f32_16x16x4_f32 v[16:19], v58, v59, v[16:19]
	s_waitcnt lgkmcnt(5)
	v_mfma_f32_16x16x4_f32 v[4:7], v45, v49, v[4:7]
	ds_read_b32 v59, v68 offset:176
	ds_read_b32 v55, v67 offset:36096
	ds_read_b32 v56, v67 offset:36160
	ds_read_b32 v57, v67 offset:36224
	ds_read_b32 v58, v67 offset:36288
	v_mfma_f32_16x16x4_f32 v[8:11], v46, v49, v[8:11]
	v_mfma_f32_16x16x4_f32 v[12:15], v47, v49, v[12:15]
	v_mfma_f32_16x16x4_f32 v[16:19], v48, v49, v[16:19]
	s_waitcnt lgkmcnt(5)
	v_mfma_f32_16x16x4_f32 v[4:7], v50, v54, v[4:7]
	ds_read_b32 v49, v68 offset:192
	ds_read_b32 v45, v67 offset:37120
	ds_read_b32 v46, v67 offset:37184
	ds_read_b32 v47, v67 offset:37248
	ds_read_b32 v48, v67 offset:37312
	v_mfma_f32_16x16x4_f32 v[8:11], v51, v54, v[8:11]
	v_mfma_f32_16x16x4_f32 v[12:15], v52, v54, v[12:15]
	v_mfma_f32_16x16x4_f32 v[16:19], v53, v54, v[16:19]
	s_waitcnt lgkmcnt(5)
	v_mfma_f32_16x16x4_f32 v[4:7], v55, v59, v[4:7]
	ds_read_b32 v54, v68 offset:208
	ds_read_b32 v50, v67 offset:38144
	ds_read_b32 v51, v67 offset:38208
	ds_read_b32 v52, v67 offset:38272
	ds_read_b32 v53, v67 offset:38336
	v_mfma_f32_16x16x4_f32 v[8:11], v56, v59, v[8:11]
	v_mfma_f32_16x16x4_f32 v[12:15], v57, v59, v[12:15]
	v_mfma_f32_16x16x4_f32 v[16:19], v58, v59, v[16:19]
	s_waitcnt lgkmcnt(5)
	v_mfma_f32_16x16x4_f32 v[4:7], v45, v49, v[4:7]
	ds_read_b32 v59, v68 offset:224
	ds_read_b32 v55, v67 offset:39168
	ds_read_b32 v56, v67 offset:39232
	ds_read_b32 v57, v67 offset:39296
	ds_read_b32 v58, v67 offset:39360
	v_mfma_f32_16x16x4_f32 v[8:11], v46, v49, v[8:11]
	v_mfma_f32_16x16x4_f32 v[12:15], v47, v49, v[12:15]
	v_mfma_f32_16x16x4_f32 v[16:19], v48, v49, v[16:19]
	s_waitcnt lgkmcnt(5)
	v_mfma_f32_16x16x4_f32 v[4:7], v50, v54, v[4:7]
	ds_read_b32 v49, v68 offset:240
	ds_read_b32 v45, v67 offset:40192
	ds_read_b32 v46, v67 offset:40256
	ds_read_b32 v47, v67 offset:40320
	ds_read_b32 v48, v67 offset:40384
	v_mfma_f32_16x16x4_f32 v[8:11], v51, v54, v[8:11]
	v_mfma_f32_16x16x4_f32 v[12:15], v52, v54, v[12:15]
	v_mfma_f32_16x16x4_f32 v[16:19], v53, v54, v[16:19]
	s_waitcnt lgkmcnt(5)
	v_mfma_f32_16x16x4_f32 v[4:7], v55, v59, v[4:7]
	v_mfma_f32_16x16x4_f32 v[8:11], v56, v59, v[8:11]
	v_mfma_f32_16x16x4_f32 v[12:15], v57, v59, v[12:15]
	v_mfma_f32_16x16x4_f32 v[16:19], v58, v59, v[16:19]
	s_waitcnt lgkmcnt(0)
	v_mfma_f32_16x16x4_f32 v[4:7], v45, v49, v[4:7]
	v_mfma_f32_16x16x4_f32 v[8:11], v46, v49, v[8:11]
	v_mfma_f32_16x16x4_f32 v[12:15], v47, v49, v[12:15]
	v_mfma_f32_16x16x4_f32 v[16:19], v48, v49, v[16:19]
	s_nop 7
	s_nop 3
	v_mul_f32_e32 v4, v20, v4
	v_mul_f32_e32 v5, v21, v5
	v_mul_f32_e32 v6, v22, v6
	v_mul_f32_e32 v7, v23, v7
	v_mul_f32_e32 v8, v24, v8
	v_mul_f32_e32 v9, v25, v9
	v_mul_f32_e32 v10, v26, v10
	v_mul_f32_e32 v11, v27, v11
	v_mul_f32_e32 v12, v28, v12
	v_mul_f32_e32 v13, v29, v13
	v_mul_f32_e32 v14, v30, v14
	v_mul_f32_e32 v15, v31, v15
	v_mul_f32_e32 v16, v32, v16
	v_mul_f32_e32 v17, v33, v17
	v_mul_f32_e32 v18, v34, v18
	v_mul_f32_e32 v19, v35, v19
	v_sin_f32_e32 v4, v4
	v_sin_f32_e32 v5, v5
	v_sin_f32_e32 v6, v6
	v_sin_f32_e32 v7, v7
	v_sin_f32_e32 v8, v8
	v_sin_f32_e32 v9, v9
	v_sin_f32_e32 v10, v10
	v_sin_f32_e32 v11, v11
	v_sin_f32_e32 v12, v12
	v_sin_f32_e32 v13, v13
	v_sin_f32_e32 v14, v14
	v_sin_f32_e32 v15, v15
	v_sin_f32_e32 v16, v16
	v_sin_f32_e32 v17, v17
	v_sin_f32_e32 v18, v18
	v_sin_f32_e32 v19, v19
	s_nop 1
	v_bfe_u32 v76, v4, 16, 1
	v_bfe_u32 v77, v5, 16, 1
	v_bfe_u32 v78, v6, 16, 1
	v_bfe_u32 v79, v7, 16, 1
	v_add3_u32 v4, v4, v76, s30
	v_add3_u32 v5, v5, v77, s30
	v_add3_u32 v6, v6, v78, s30
	v_add3_u32 v7, v7, v79, s30
	v_perm_b32 v4, v5, v4, s31
	v_perm_b32 v5, v7, v6, s31
	global_store_dwordx2 v92, v[4:5], s[26:27] offset:0
	v_bfe_u32 v76, v8, 16, 1
	v_bfe_u32 v77, v9, 16, 1
	v_bfe_u32 v78, v10, 16, 1
	v_bfe_u32 v79, v11, 16, 1
	v_add3_u32 v8, v8, v76, s30
	v_add3_u32 v9, v9, v77, s30
	v_add3_u32 v10, v10, v78, s30
	v_add3_u32 v11, v11, v79, s30
	v_perm_b32 v8, v9, v8, s31
	v_perm_b32 v9, v11, v10, s31
	global_store_dwordx2 v92, v[8:9], s[26:27] offset:32
	v_bfe_u32 v76, v12, 16, 1
	v_bfe_u32 v77, v13, 16, 1
	v_bfe_u32 v78, v14, 16, 1
	v_bfe_u32 v79, v15, 16, 1
	v_add3_u32 v12, v12, v76, s30
	v_add3_u32 v13, v13, v77, s30
	v_add3_u32 v14, v14, v78, s30
	v_add3_u32 v15, v15, v79, s30
	v_perm_b32 v12, v13, v12, s31
	v_perm_b32 v13, v15, v14, s31
	global_store_dwordx2 v92, v[12:13], s[26:27] offset:64
	v_bfe_u32 v76, v16, 16, 1
	v_bfe_u32 v77, v17, 16, 1
	v_bfe_u32 v78, v18, 16, 1
	v_bfe_u32 v79, v19, 16, 1
	v_add3_u32 v16, v16, v76, s30
	v_add3_u32 v17, v17, v77, s30
	v_add3_u32 v18, v18, v78, s30
	v_add3_u32 v19, v19, v79, s30
	v_perm_b32 v16, v17, v16, s31
	v_perm_b32 v17, v19, v18, s31
	global_store_dwordx2 v92, v[16:17], s[26:27] offset:96
	s_branch .Lmy_padb
	s_nop 0
	s_nop 0
	s_nop 0
	s_nop 0
	s_nop 0
	s_nop 0
.Lmy_padb:
.LBB0_39:
	s_or_b64 exec, exec, s[8:9]
	s_movk_i32 s0, 0x1040
	v_cmp_gt_i32_e32 vcc, s0, v66
	s_barrier
	s_and_saveexec_b64 s[4:5], vcc
	s_cbranch_execz .LBB0_129
	s_movk_i32 s0, 0x4100
	v_mad_u32_u24 v3, v200, s0, 0
	v_lshrrev_b32_e32 v1, 4, v64
	s_movk_i32 s0, 0x104
	v_mov_b32_e32 v5, 0x410
	s_add_u32 s8, s56, 0x1c000000
	v_mad_u32_u24 v67, v1, s0, v5
	v_mov_b32_e32 v5, 0x820
	s_addc_u32 s9, s57, 0
	v_mad_u32_u24 v74, v1, s0, v5
	v_mov_b32_e32 v5, 0xc30
	s_add_u32 s24, s56, 0x1dc00000
	v_mad_u32_u24 v76, v1, s0, v5
	v_mov_b32_e32 v5, 0x1040
	s_addc_u32 s25, s57, 0
	v_mad_u32_u24 v78, v1, s0, v5
	v_mov_b32_e32 v5, 0x1450
	s_add_u32 s26, s56, 0x1e720000
	v_mad_u32_u24 v80, v1, s0, v5
	v_mov_b32_e32 v5, 0x1860
	v_readlane_b32 s36, v244, 0
	s_addc_u32 s27, s57, 0
	v_mad_u32_u24 v82, v1, s0, v5
	v_mov_b32_e32 v5, 0x1c70
	s_lshl_b32 s29, s29, 3
	v_readlane_b32 s40, v244, 4
	v_mad_u32_u24 v84, v1, s0, v5
	v_mov_b32_e32 v5, 0x2080
	v_readlane_b32 s41, v244, 5
	s_add_u32 s30, s40, 0xfffff000
	v_mad_u32_u24 v86, v1, s0, v5
	v_mov_b32_e32 v5, 0x2490
	s_addc_u32 s31, s41, -1
	v_and_b32_e32 v2, 60, v2
	v_mad_u32_u24 v88, v1, s0, v5
	v_mov_b32_e32 v5, 0x28a0
	v_readlane_b32 s37, v244, 1
	s_cmp_lg_u64 s[16:17], 0
	v_lshlrev_b32_e32 v14, 2, v2
	v_or_b32_e32 v65, 4, v1
	v_or_b32_e32 v73, 8, v1
	v_or_b32_e32 v75, 12, v1
	v_or_b32_e32 v77, 16, v1
	v_or_b32_e32 v79, 20, v1
	v_or_b32_e32 v81, 24, v1
	v_or_b32_e32 v83, 28, v1
	v_or_b32_e32 v85, 32, v1
	v_or_b32_e32 v87, 36, v1
	v_or_b32_e32 v89, 40, v1
	v_mad_u32_u24 v90, v1, s0, v5
	v_or_b32_e32 v91, 44, v1
	v_or_b32_e32 v92, 48, v1
	v_or_b32_e32 v93, 52, v1
	v_or_b32_e32 v94, 56, v1
	v_or_b32_e32 v95, 60, v1
	s_cselect_b64 s[36:37], -1, 0
	s_lshl_b32 s0, s28, 9
	s_lshl_b32 s1, s34, 9
	v_add_u32_e32 v57, v3, v14
	v_lshlrev_b32_e32 v2, 12, v1
	v_mov_b32_e32 v15, 0
	v_lshlrev_b32_e32 v4, 12, v65
	v_lshlrev_b32_e32 v6, 12, v73
	v_lshlrev_b32_e32 v8, 12, v75
	v_lshlrev_b32_e32 v10, 12, v77
	v_lshlrev_b32_e32 v12, 12, v79
	v_lshlrev_b32_e32 v36, 12, v81
	v_lshlrev_b32_e32 v38, 12, v83
	v_lshlrev_b32_e32 v40, 12, v85
	v_lshlrev_b32_e32 v42, 12, v87
	v_lshlrev_b32_e32 v44, 12, v89
	v_lshlrev_b32_e32 v46, 12, v91
	v_lshlrev_b32_e32 v48, 12, v92
	v_lshlrev_b32_e32 v50, 12, v93
	v_lshlrev_b32_e32 v52, 12, v94
	v_lshlrev_b32_e32 v54, 12, v95
	v_lshl_add_u32 v96, v64, 2, v3
	v_readlane_b32 s42, v244, 6
	v_readlane_b32 s43, v244, 7
	v_mov_b32_e32 v3, 0xfffc0000
	s_sub_i32 s33, s0, s1
	s_lshl_b32 s0, s28, 4
	s_lshl_b32 s1, s34, 4
	v_mul_u32_u24_e32 v63, 0x104, v1
	v_lshl_add_u64 v[16:17], s[44:45], 0, v[14:15]
	v_lshl_add_u64 v[18:19], s[42:43], 0, v[14:15]
	v_lshl_add_u64 v[20:21], s[18:19], 0, v[14:15]
	s_mov_b64 s[18:19], 0
	v_lshl_add_u32 v22, v66, 6, v3
	v_lshlrev_b32_e32 v97, 1, v66
	s_sub_i32 s34, s0, s1
	s_movk_i32 s35, 0xbff
	s_movk_i32 s44, 0xfff
	v_lshlrev_b32_e32 v24, 2, v2
	v_lshlrev_b32_e32 v26, 2, v4
	v_lshlrev_b32_e32 v28, 2, v6
	v_lshlrev_b32_e32 v30, 2, v8
	v_lshlrev_b32_e32 v32, 2, v10
	v_lshlrev_b32_e32 v34, 2, v12
	v_lshlrev_b32_e32 v36, 2, v36
	v_lshlrev_b32_e32 v38, 2, v38
	v_lshlrev_b32_e32 v40, 2, v40
	v_lshlrev_b32_e32 v42, 2, v42
	v_lshlrev_b32_e32 v44, 2, v44
	v_lshlrev_b32_e32 v46, 2, v46
	v_lshlrev_b32_e32 v48, 2, v48
	v_lshlrev_b32_e32 v50, 2, v50
	v_lshlrev_b32_e32 v52, 2, v52
	v_lshlrev_b32_e32 v54, 2, v54
	s_movk_i32 s45, 0x7fff
	s_mov_b32 s46, 0xffff0000
	s_movk_i32 s47, 0x13ff
	s_movk_i32 s60, 0x103f
	v_readlane_b32 s38, v244, 2
	v_readlane_b32 s39, v244, 3
	s_branch .LBB0_44
